# S5 pass 2: U-tile prefetch two steps ahead with two alternating buffers and counted wait
# baseline (speedup 1.0000x reference)
.LBB0_1089:
	s_or_b64 exec, exec, s[16:17]
	s_and_b32 s16, s18, 0x2000
	s_and_b32 s17, s19, 0x7f
	s_add_u32 s14, s14, s16
	s_addc_u32 s15, s15, 0
	v_lshl_add_u64 v[50:51], s[14:15], 0, v[60:61]
	v_lshlrev_b64 v[50:51], 12, v[50:51]
	v_lshl_or_b32 v50, s17, 5, v50
	v_lshl_add_u64 v[80:81], v[74:75], 0, v[50:51]
	v_lshl_add_u64 v[50:51], s[14:15], 0, v[70:71]
	v_lshlrev_b64 v[82:83], 11, v[50:51]
	v_or_b32_e32 v50, v60, v82
	v_lshl_or_b32 v82, s17, 4, v50
	v_lshlrev_b64 v[50:51], 1, v[82:83]
	s_waitcnt vmcnt(0) lgkmcnt(0)
	v_mov_b32_e32 v0, v77
	v_pk_mov_b32 v[78:79], v[76:77], v[76:77] op_sel:[1,0]
	v_lshl_add_u64 v[84:85], s[8:9], 0, v[50:51]
	v_lshl_add_u64 v[86:87], s[6:7], 0, v[50:51]
	v_mov_b32_e32 v50, 0
	v_mov_b32_e32 v51, 0
	v_mov_b32_e32 v52, 0
	v_mov_b32_e32 v53, 0
	v_mov_b32_e32 v144, 0
	v_mov_b32_e32 v145, 0
	v_mov_b32_e32 v146, 0
	v_mov_b32_e32 v147, 0
	s_and_saveexec_b64 s[16:17], s[4:5]
	global_load_dwordx4 v[50:53], v[80:81], off
	s_or_b64 exec, exec, s[16:17]
	s_mov_b64 s[98:99], 0x10000
	v_lshl_add_u64 v[80:81], v[80:81], 0, s[98:99]
	s_branch .LBB0_1091
.LBB0_1090:
	s_mov_b64 s[100:101], 0x2000
	global_load_ushort v102, v[86:87], off
	v_lshl_add_u64 v[106:107], v[86:87], 0, s[100:101]
	global_load_ushort v103, v[106:107], off offset:-4096
	global_load_ushort v104, v[106:107], off
	v_lshl_add_u64 v[106:107], v[106:107], 0, s[100:101]
	global_load_ushort v105, v[106:107], off offset:-4096
	s_and_saveexec_b64 s[16:17], s[4:5]
	s_bitcmp1_b32 s20, 4
	s_cbranch_scc1 .Ls5b_odd_ld
	global_load_dwordx4 v[144:147], v[80:81], off
	s_branch .Ls5b_ld_done
.Ls5b_odd_ld:
	global_load_dwordx4 v[50:53], v[80:81], off
.Ls5b_ld_done:
	s_or_b64 exec, exec, s[16:17]
	v_mfma_f32_16x16x32_bf16 v[94:97], v[54:57], v[2:5], 0
	v_add_u32_e32 v93, 0x400, v59
	s_mov_b64 s[22:23], 0x10000
	s_mov_b64 s[16:17], 0x8000
	v_mfma_f32_16x16x32_bf16 v[98:101], v[54:57], v[6:9], 0
	s_nop 7
	ds_write2_b32 v59, v94, v98 offset1:16
	ds_write2_b32 v59, v95, v99 offset0:132 offset1:148
	ds_write2_b32 v93, v96, v100 offset0:8 offset1:24
	ds_write2_b32 v93, v97, v101 offset0:140 offset1:156
	v_mfma_f32_16x16x32_bf16 v[94:97], v[54:57], v[10:13], 0
	s_add_i32 s20, s20, 16
	v_lshl_add_u64 v[80:81], v[80:81], 0, s[22:23]
	s_and_b64 vcc, exec, s[14:15]
	v_mfma_f32_16x16x32_bf16 v[98:101], v[54:57], v[14:17], 0
	s_nop 7
	ds_write2_b32 v59, v94, v98 offset0:32 offset1:48
	ds_write2_b32 v59, v95, v99 offset0:164 offset1:180
	ds_write2_b32 v93, v96, v100 offset0:40 offset1:56
	ds_write2_b32 v93, v97, v101 offset0:172 offset1:188
	v_mfma_f32_16x16x32_bf16 v[94:97], v[54:57], v[18:21], 0
	v_mfma_f32_16x16x32_bf16 v[98:101], v[54:57], v[22:25], 0
	s_nop 7
	ds_write2_b32 v59, v94, v98 offset0:64 offset1:80
	ds_write2_b32 v59, v95, v99 offset0:196 offset1:212
	ds_write2_b32 v93, v96, v100 offset0:72 offset1:88
	ds_write2_b32 v93, v97, v101 offset0:204 offset1:220
	v_mfma_f32_16x16x32_bf16 v[94:97], v[54:57], v[26:29], 0
	v_mfma_f32_16x16x32_bf16 v[54:57], v[54:57], v[30:33], 0
	s_nop 7
	ds_write2_b32 v59, v94, v54 offset0:96 offset1:112
	ds_write2_b32 v59, v95, v55 offset0:228 offset1:244
	ds_write2_b32 v93, v96, v56 offset0:104 offset1:120
	ds_write2_b32 v93, v97, v57 offset0:236 offset1:252
	ds_read_b32 v110, v90
	ds_read_b32 v111, v90 offset:256
	ds_read_b32 v112, v90 offset:528
	ds_read_b32 v113, v90 offset:784
	ds_read_b32 v114, v90 offset:1056
	ds_read_b32 v115, v90 offset:1312
	ds_read_b32 v116, v90 offset:1584
	ds_read_b32 v117, v90 offset:1840
	ds_read_b32 v118, v90 offset:2112
	ds_read_b32 v119, v90 offset:2368
	ds_read_b32 v120, v90 offset:2640
	ds_read_b32 v121, v90 offset:2896
	ds_read_b32 v122, v90 offset:3168
	ds_read_b32 v123, v90 offset:3424
	ds_read_b32 v124, v90 offset:3696
	ds_read_b32 v125, v90 offset:3952
	ds_read_b32 v126, v90 offset:4224
	ds_read_b32 v127, v90 offset:4480
	ds_read_b32 v128, v90 offset:4752
	ds_read_b32 v129, v90 offset:5008
	ds_read_b32 v130, v90 offset:5280
	ds_read_b32 v131, v90 offset:5536
	ds_read_b32 v132, v90 offset:5808
	ds_read_b32 v133, v90 offset:6064
	ds_read_b32 v134, v90 offset:6336
	ds_read_b32 v135, v90 offset:6592
	ds_read_b32 v136, v90 offset:6864
	ds_read_b32 v137, v90 offset:7120
	ds_read_b32 v138, v90 offset:7392
	ds_read_b32 v139, v90 offset:7648
	ds_read_b32 v140, v90 offset:7920
	ds_read_b32 v141, v90 offset:8176
	s_waitcnt lgkmcnt(0)
	v_fma_f32 v54, -v77, v89, v110
	v_fma_f32 v55, v77, v88, v111
	v_fma_f32 v56, v76, v88, v54
	v_fma_f32 v57, v76, v89, v55
	v_fma_f32 v54, -v77, v57, v112
	v_fma_f32 v55, v77, v56, v113
	v_cvt_pk_bf16_f32 v142, v56, v57
	ds_write_b16 v91, v142 offset:8448
	ds_write_b16_d16_hi v91, v142 offset:8576
	v_fma_f32 v88, v76, v56, v54
	v_fma_f32 v89, v76, v57, v55
	v_fma_f32 v54, -v77, v89, v114
	v_fma_f32 v55, v77, v88, v115
	v_cvt_pk_bf16_f32 v142, v88, v89
	ds_write_b16 v91, v142 offset:8720
	ds_write_b16_d16_hi v91, v142 offset:8848
	v_fma_f32 v56, v76, v88, v54
	v_fma_f32 v57, v76, v89, v55
	v_fma_f32 v54, -v77, v57, v116
	v_fma_f32 v55, v77, v56, v117
	v_cvt_pk_bf16_f32 v142, v56, v57
	ds_write_b16 v91, v142 offset:8992
	ds_write_b16_d16_hi v91, v142 offset:9120
	v_fma_f32 v88, v76, v56, v54
	v_fma_f32 v89, v76, v57, v55
	v_fma_f32 v54, -v77, v89, v118
	v_fma_f32 v55, v77, v88, v119
	v_cvt_pk_bf16_f32 v142, v88, v89
	ds_write_b16 v91, v142 offset:9264
	ds_write_b16_d16_hi v91, v142 offset:9392
	v_fma_f32 v56, v76, v88, v54
	v_fma_f32 v57, v76, v89, v55
	v_fma_f32 v54, -v77, v57, v120
	v_fma_f32 v55, v77, v56, v121
	v_cvt_pk_bf16_f32 v142, v56, v57
	ds_write_b16 v91, v142 offset:9536
	ds_write_b16_d16_hi v91, v142 offset:9664
	v_fma_f32 v88, v76, v56, v54
	v_fma_f32 v89, v76, v57, v55
	v_fma_f32 v54, -v77, v89, v122
	v_fma_f32 v55, v77, v88, v123
	v_cvt_pk_bf16_f32 v142, v88, v89
	ds_write_b16 v91, v142 offset:9808
	ds_write_b16_d16_hi v91, v142 offset:9936
	v_fma_f32 v56, v76, v88, v54
	v_fma_f32 v57, v76, v89, v55
	v_fma_f32 v54, -v77, v57, v124
	v_fma_f32 v55, v77, v56, v125
	v_cvt_pk_bf16_f32 v142, v56, v57
	ds_write_b16 v91, v142 offset:10080
	ds_write_b16_d16_hi v91, v142 offset:10208
	v_fma_f32 v88, v76, v56, v54
	v_fma_f32 v89, v76, v57, v55
	v_fma_f32 v54, -v77, v89, v126
	v_fma_f32 v55, v77, v88, v127
	v_cvt_pk_bf16_f32 v142, v88, v89
	ds_write_b16 v91, v142 offset:10352
	ds_write_b16_d16_hi v91, v142 offset:10480
	v_fma_f32 v56, v76, v88, v54
	v_fma_f32 v57, v76, v89, v55
	v_fma_f32 v54, -v77, v57, v128
	v_fma_f32 v55, v77, v56, v129
	v_cvt_pk_bf16_f32 v142, v56, v57
	ds_write_b16 v91, v142 offset:10624
	ds_write_b16_d16_hi v91, v142 offset:10752
	v_fma_f32 v88, v76, v56, v54
	v_fma_f32 v89, v76, v57, v55
	v_fma_f32 v54, -v77, v89, v130
	v_fma_f32 v55, v77, v88, v131
	v_cvt_pk_bf16_f32 v142, v88, v89
	ds_write_b16 v91, v142 offset:10896
	ds_write_b16_d16_hi v91, v142 offset:11024
	v_fma_f32 v56, v76, v88, v54
	v_fma_f32 v57, v76, v89, v55
	v_fma_f32 v54, -v77, v57, v132
	v_fma_f32 v55, v77, v56, v133
	v_cvt_pk_bf16_f32 v142, v56, v57
	ds_write_b16 v91, v142 offset:11168
	ds_write_b16_d16_hi v91, v142 offset:11296
	v_fma_f32 v88, v76, v56, v54
	v_fma_f32 v89, v76, v57, v55
	v_fma_f32 v54, -v77, v89, v134
	v_fma_f32 v55, v77, v88, v135
	v_cvt_pk_bf16_f32 v142, v88, v89
	ds_write_b16 v91, v142 offset:11440
	ds_write_b16_d16_hi v91, v142 offset:11568
	v_fma_f32 v56, v76, v88, v54
	v_fma_f32 v57, v76, v89, v55
	v_fma_f32 v54, -v77, v57, v136
	v_fma_f32 v55, v77, v56, v137
	v_cvt_pk_bf16_f32 v142, v56, v57
	ds_write_b16 v91, v142 offset:11712
	ds_write_b16_d16_hi v91, v142 offset:11840
	v_fma_f32 v88, v76, v56, v54
	v_fma_f32 v89, v76, v57, v55
	v_fma_f32 v54, -v77, v89, v138
	v_fma_f32 v55, v77, v88, v139
	v_cvt_pk_bf16_f32 v142, v88, v89
	ds_write_b16 v91, v142 offset:11984
	ds_write_b16_d16_hi v91, v142 offset:12112
	v_fma_f32 v56, v76, v88, v54
	v_fma_f32 v57, v76, v89, v55
	v_fma_f32 v54, -v77, v57, v140
	v_fma_f32 v55, v77, v56, v141
	v_cvt_pk_bf16_f32 v142, v56, v57
	ds_write_b16 v91, v142 offset:12256
	ds_write_b16_d16_hi v91, v142 offset:12384
	v_fma_f32 v88, v76, v56, v54
	v_fma_f32 v89, v76, v57, v55
	v_cvt_pk_bf16_f32 v142, v88, v89
	ds_write_b16 v91, v142 offset:12528
	ds_write_b16_d16_hi v91, v142 offset:12656
	ds_read_b128 v[54:57], v63 offset:8448
	ds_read_b128 v[94:97], v63 offset:8512
	s_waitcnt lgkmcnt(0)
	v_mfma_f32_16x16x32_bf16 v[54:57], v[54:57], v[34:37], 0
	v_lshl_add_u64 v[86:87], v[86:87], 0, s[22:23]
	s_waitcnt vmcnt(1)
	v_lshlrev_b32_e32 v93, 16, v102
	v_mfma_f32_16x16x32_bf16 v[54:57], v[94:97], v[38:41], v[54:57]
	ds_read_b128 v[94:97], v63 offset:8576
	s_waitcnt lgkmcnt(0)
	v_mfma_f32_16x16x32_bf16 v[54:57], v[94:97], v[42:45], v[54:57]
	ds_read_b128 v[94:97], v63 offset:8640
	s_waitcnt lgkmcnt(0)
	v_mfma_f32_16x16x32_bf16 v[54:57], v[94:97], v[46:49], v[54:57]
	v_lshlrev_b64 v[94:95], 1, v[82:83]
	v_or_b32_e32 v96, 0x1000, v94
	v_mov_b32_e32 v97, v95
	s_nop 4
	v_fma_f32 v54, v92, v93, v54
	v_mul_f32_e32 v93, 0x3d372713, v54
	v_mul_f32_e32 v93, v54, v93
	v_fma_f32 v93, v54, v93, v54
	v_mul_f32_e32 v93, 0x3f4c422a, v93
	v_add_f32_e32 v93, v93, v93
	v_mul_f32_e32 v93, 0x3fb8aa3b, v93
	v_exp_f32_e32 v93, v93
	v_lshl_add_u64 v[98:99], s[6:7], 0, v[96:97]
	v_lshl_add_u64 v[82:83], v[82:83], 0, s[16:17]
	v_add_f32_e32 v93, 1.0, v93
	v_rcp_f32_e32 v93, v93
	s_nop 0
	v_sub_f32_e32 v93, 1.0, v93
	v_mul_f32_e32 v54, v54, v93
	v_bfe_u32 v93, v54, 16, 1
	v_add3_u32 v54, v54, v93, s97
	global_store_short_d16_hi v[84:85], v54, off
	v_lshl_add_u64 v[84:85], v[84:85], 0, s[22:23]
	v_lshlrev_b32_e32 v54, 16, v103
	v_fma_f32 v54, v92, v54, v55
	v_mul_f32_e32 v55, 0x3d372713, v54
	v_mul_f32_e32 v55, v54, v55
	v_fma_f32 v55, v54, v55, v54
	v_mul_f32_e32 v55, 0x3f4c422a, v55
	v_add_f32_e32 v55, v55, v55
	v_mul_f32_e32 v55, 0x3fb8aa3b, v55
	v_exp_f32_e32 v55, v55
	s_nop 0
	v_add_f32_e32 v55, 1.0, v55
	v_rcp_f32_e32 v55, v55
	s_nop 0
	v_sub_f32_e32 v55, 1.0, v55
	v_mul_f32_e32 v54, v54, v55
	v_bfe_u32 v55, v54, 16, 1
	v_add3_u32 v93, v54, v55, s97
	v_lshl_add_u64 v[54:55], s[8:9], 0, v[96:97]
	global_store_short_d16_hi v[54:55], v93, off
	v_or_b32_e32 v54, 0x2000, v94
	v_mov_b32_e32 v55, v95
	v_lshl_add_u64 v[96:97], s[6:7], 0, v[54:55]
	v_lshl_add_u64 v[54:55], s[8:9], 0, v[54:55]
	v_or_b32_e32 v94, 0x3000, v94
	v_lshlrev_b32_e32 v93, 16, v104
	v_fma_f32 v56, v92, v93, v56
	v_mul_f32_e32 v93, 0x3d372713, v56
	v_mul_f32_e32 v93, v56, v93
	v_fma_f32 v93, v56, v93, v56
	v_mul_f32_e32 v93, 0x3f4c422a, v93
	v_add_f32_e32 v93, v93, v93
	v_mul_f32_e32 v93, 0x3fb8aa3b, v93
	v_exp_f32_e32 v93, v93
	s_nop 0
	v_add_f32_e32 v93, 1.0, v93
	v_rcp_f32_e32 v93, v93
	s_nop 0
	v_sub_f32_e32 v93, 1.0, v93
	v_mul_f32_e32 v56, v56, v93
	v_bfe_u32 v93, v56, 16, 1
	v_add3_u32 v56, v56, v93, s97
	global_store_short_d16_hi v[54:55], v56, off
	v_lshl_add_u64 v[54:55], s[6:7], 0, v[94:95]
	v_lshlrev_b32_e32 v54, 16, v105
	v_fmac_f32_e32 v57, v92, v54
	v_mul_f32_e32 v54, 0x3d372713, v57
	v_mul_f32_e32 v54, v57, v54
	v_fma_f32 v54, v57, v54, v57
	v_mul_f32_e32 v54, 0x3f4c422a, v54
	v_add_f32_e32 v54, v54, v54
	v_mul_f32_e32 v54, 0x3fb8aa3b, v54
	v_exp_f32_e32 v54, v54
	s_nop 0
	v_add_f32_e32 v54, 1.0, v54
	v_rcp_f32_e32 v54, v54
	s_nop 0
	v_sub_f32_e32 v54, 1.0, v54
	v_mul_f32_e32 v54, v57, v54
	v_bfe_u32 v55, v54, 16, 1
	v_add3_u32 v56, v54, v55, s97
	v_lshl_add_u64 v[54:55], s[8:9], 0, v[94:95]
	global_store_short_d16_hi v[54:55], v56, off
	s_bitcmp1_b32 s20, 4
	s_cbranch_scc0 .Ls5b_from_bb
	v_mov_b32_e32 v54, v50
	v_mov_b32_e32 v55, v51
	v_mov_b32_e32 v56, v52
	v_mov_b32_e32 v57, v53
	s_branch .Ls5b_cp_done
.Ls5b_from_bb:
	v_mov_b32_e32 v54, v144
	v_mov_b32_e32 v55, v145
	v_mov_b32_e32 v56, v146
	v_mov_b32_e32 v57, v147

.LBB0_1091:
	s_cmpk_gt_u32 s20, 0x3ef
	s_cselect_b64 s[14:15], -1, 0
	s_branch .LBB0_1090
